# mixers: WGs with blockIdx bit 8 set walk their NA items before their MLA items (rounds 1,2,3,0), variant of co-scheduling class choice
# baseline (speedup 1.0000x reference)
.LBB0_209:
	v_writelane_b32 v221, s20, 61
	s_movk_i32 s1, 0x800
	s_movk_i32 s0, 0xfa00
	s_cmpk_lt_u32 s20, 0x800
	s_cselect_b32 s1, s1, s0
	s_movk_i32 s0, 0xf200
	s_cmpk_ge_u32 s20, 0xe00
	s_cselect_b32 s1, s0, s1
	s_cmpk_lt_u32 s20, 0x1000
	s_cselect_b32 s1, s1, 0
	v_readlane_b32 s0, v226, 0
	s_nop 0
	s_bitcmp1_b32 s0, 8
	s_cselect_b32 s1, s1, 0
	s_add_i32 s20, s20, s1
	s_cmp_ge_i32 s20, s14
	s_mov_b64 s[0:1], -1
	s_cbranch_scc0 .LBB0_211
	s_sub_i32 s0, s20, s14
	s_lshl_b32 s0, s0, 5
	v_mov_b32_e32 v10, v196
	s_and_b32 s2, s0, 0x7fffff80
	s_and_b32 s5, s20, 3
	v_lshrrev_b32_e32 v0, 2, v10
	s_lshl_b64 s[0:1], s[2:3], 10
	v_and_b32_e32 v0, 12, v0
	s_add_u32 s2, s15, s0
	v_lshrrev_b32_e64 v0, v0, s57
	s_addc_u32 s7, s21, s1
	s_lshl_b32 s4, s5, 8
	v_xor_b32_e32 v0, v0, v10
	s_add_u32 s6, s2, s4
	v_ashrrev_i32_e32 v2, 2, v10
	v_lshlrev_b32_e32 v0, 4, v0
	s_addc_u32 s7, s7, 0
	v_and_b32_e32 v0, 48, v0
	v_ashrrev_i32_e32 v3, 31, v2
	v_lshl_add_u64 v[4:5], s[6:7], 0, v[0:1]
	v_lshlrev_b64 v[6:7], 10, v[2:3]
	v_lshl_add_u64 v[70:71], v[4:5], 0, v[6:7]
	v_add_u32_e32 v6, 64, v2
	s_lshl_b32 s2, s5, 15
	v_readlane_b32 s8, v224, 11
	v_ashrrev_i32_e32 v7, 31, v6
	s_add_u32 s8, s8, s2
	v_readlane_b32 s2, v224, 12
	v_lshlrev_b64 v[8:9], 10, v[6:7]
	s_addc_u32 s9, s2, 0
	v_lshl_add_u64 v[72:73], v[4:5], 0, v[8:9]
	v_and_b32_e32 v8, 15, v10
	v_lshlrev_b64 v[4:5], 8, v[6:7]
	v_lshl_add_u32 v12, v10, 4, 0
	v_lshrrev_b32_e32 v6, 1, v10
	s_mov_b32 s2, 0x3ffffc0
	v_lshlrev_b64 v[2:3], 8, v[2:3]
	v_and_or_b32 v13, v6, s2, v8
	v_readfirstlane_b32 s2, v12
	v_add_u32_e32 v8, 0x1000, v12
	v_lshl_add_u64 v[2:3], s[8:9], 0, v[2:3]
	v_and_b32_e32 v6, 12, v10
	s_mov_b32 m0, s2
	v_readfirstlane_b32 s6, v8
	v_lshl_add_u64 v[74:75], v[2:3], 0, v[0:1]
	v_add_u32_e32 v2, 0x2000, v12
	v_lshrrev_b32_e32 v11, 4, v10
	v_lshl_add_u64 v[4:5], s[8:9], 0, v[4:5]
	v_lshrrev_b32_e64 v6, v6, s57
	global_load_lds_dwordx4 v[70:71], off
	s_mov_b32 m0, s6
	v_readfirstlane_b32 s7, v2
	v_add_u32_e32 v2, 0x3000, v12
	v_xor_b32_e32 v6, v6, v11
	global_load_lds_dwordx4 v[72:73], off
	v_lshl_add_u64 v[76:77], v[4:5], 0, v[0:1]
	s_mov_b32 m0, s7
	v_readfirstlane_b32 s8, v2
	v_add_u32_e32 v4, 0x4000, v12
	v_lshlrev_b32_e32 v11, 4, v6
	v_lshlrev_b32_e32 v6, 6, v10
	global_load_lds_dwordx4 v[74:75], off
	s_mov_b32 m0, s8
	v_readfirstlane_b32 s9, v4
	v_and_b32_e32 v10, 0x13c0, v6
	v_lshl_add_u64 v[6:7], v[70:71], 0, 64
	global_load_lds_dwordx4 v[76:77], off
	s_mov_b32 m0, s9
	v_add_u32_e32 v4, 0x5000, v12
	global_load_lds_dwordx4 v[6:7], off
	v_readfirstlane_b32 s9, v4
	v_add_u32_e32 v6, 0x6000, v12
	v_lshl_add_u64 v[8:9], v[72:73], 0, 64
	s_mov_b32 m0, s9
	v_readfirstlane_b32 s9, v6
	v_lshl_add_u64 v[2:3], v[74:75], 0, 64
	global_load_lds_dwordx4 v[8:9], off
	s_mov_b32 m0, s9
	v_and_b32_e32 v0, 48, v11
	global_load_lds_dwordx4 v[2:3], off
	v_add_u32_e32 v2, 0x7000, v12
	v_lshl_add_u64 v[4:5], v[76:77], 0, 64
	v_readfirstlane_b32 s9, v2
	s_mov_b32 m0, s9
	v_add_u32_e32 v11, 0x8000, v12
	global_load_lds_dwordx4 v[4:5], off
	v_add_u32_e32 v14, 0xb000, v12
	v_add_u32_e32 v15, 0xa000, v12
	v_add_u32_e32 v12, 0x9000, v12
	v_readfirstlane_b32 s9, v11
	s_waitcnt vmcnt(4) lgkmcnt(0)
	s_barrier
	v_lshl_add_u64 v[2:3], v[70:71], 0, s[78:79]
	s_mov_b32 m0, s9
	v_readfirstlane_b32 s9, v12
	v_lshl_add_u64 v[4:5], v[72:73], 0, s[78:79]
	global_load_lds_dwordx4 v[2:3], off
	s_mov_b32 m0, s9
	v_readfirstlane_b32 s9, v15
	v_lshl_add_u64 v[8:9], v[74:75], 0, s[78:79]
	global_load_lds_dwordx4 v[4:5], off
	s_mov_b32 m0, s9
	v_readfirstlane_b32 s9, v14
	v_lshl_add_u64 v[6:7], v[76:77], 0, s[78:79]
	global_load_lds_dwordx4 v[8:9], off
	s_mov_b32 m0, s9
	v_add3_u32 v90, 0, v10, v0
	v_lshlrev_b32_e32 v10, 6, v13
	global_load_lds_dwordx4 v[6:7], off
	v_add3_u32 v0, 0, v10, v0
	ds_read_b128 v[2:5], v90 offset:8192
	ds_read_b128 v[6:9], v90 offset:9216
	ds_read_b128 v[10:13], v0
	ds_read_b128 v[14:17], v0 offset:1024
	ds_read_b128 v[22:25], v90 offset:10240
	ds_read_b128 v[30:33], v90 offset:11264
	ds_read_b128 v[50:53], v0 offset:2048
	ds_read_b128 v[54:57], v0 offset:3072
	v_lshl_add_u64 v[70:71], v[70:71], 0, s[84:85]
	s_waitcnt vmcnt(4) lgkmcnt(0)
	s_barrier
	s_mov_b32 m0, s2
	v_lshl_add_u64 v[72:73], v[72:73], 0, s[84:85]
	global_load_lds_dwordx4 v[70:71], off
	s_mov_b32 m0, s6
	v_lshl_add_u64 v[74:75], v[74:75], 0, s[84:85]
	global_load_lds_dwordx4 v[72:73], off
	s_mov_b32 m0, s7
	v_lshl_add_u64 v[76:77], v[76:77], 0, s[84:85]
	global_load_lds_dwordx4 v[74:75], off
	s_mov_b32 m0, s8
	s_waitcnt lgkmcnt(0)
	s_setprio 1
	v_mfma_f32_16x16x32_bf16 v[18:21], v[2:5], v[10:13], 0
	global_load_lds_dwordx4 v[76:77], off
	s_setprio 0
	ds_read_b128 v[70:73], v90 offset:24576
	s_setprio 1
	v_mfma_f32_16x16x32_bf16 v[26:29], v[6:9], v[10:13], 0
	s_lshl_b32 s2, s5, 9
	v_lshl_add_u64 v[94:95], v[146:147], 0, s[2:3]
	v_readlane_b32 s2, v224, 1
	v_mfma_f32_16x16x32_bf16 v[34:37], v[22:25], v[10:13], 0
	s_add_u32 s0, s2, s0
	v_readlane_b32 s2, v224, 2
	s_addc_u32 s1, s2, s1
	v_mfma_f32_16x16x32_bf16 v[10:13], v[30:33], v[10:13], 0
	s_mov_b32 s2, 0xfffffc0
	s_add_u32 s0, s0, s4
	s_addc_u32 s1, s1, 0
	v_mfma_f32_16x16x32_bf16 v[38:41], v[2:5], v[14:17], 0
	v_mfma_f32_16x16x32_bf16 v[42:45], v[6:9], v[14:17], 0
	v_mfma_f32_16x16x32_bf16 v[46:49], v[22:25], v[14:17], 0
	v_mfma_f32_16x16x32_bf16 v[14:17], v[30:33], v[14:17], 0
	v_mfma_f32_16x16x32_bf16 v[58:61], v[2:5], v[50:53], 0
	v_mfma_f32_16x16x32_bf16 v[62:65], v[6:9], v[50:53], 0
	v_mfma_f32_16x16x32_bf16 v[66:69], v[22:25], v[50:53], 0
	v_mfma_f32_16x16x32_bf16 v[50:53], v[30:33], v[50:53], 0
	v_mfma_f32_16x16x32_bf16 v[2:5], v[2:5], v[54:57], 0
	v_mfma_f32_16x16x32_bf16 v[6:9], v[6:9], v[54:57], 0
	v_mfma_f32_16x16x32_bf16 v[22:25], v[22:25], v[54:57], 0
	v_mfma_f32_16x16x32_bf16 v[30:33], v[30:33], v[54:57], 0
	s_setprio 0
	ds_read_b128 v[54:57], v90 offset:25600
	ds_read_b128 v[74:77], v0 offset:16384
	ds_read_b128 v[78:81], v0 offset:17408
	ds_read_b128 v[82:85], v90 offset:26624
	ds_read_b128 v[86:89], v90 offset:27648
	s_waitcnt lgkmcnt(0)
	s_setprio 1
	v_mfma_f32_16x16x32_bf16 v[18:21], v[70:73], v[74:77], v[18:21]
	v_mfma_f32_16x16x32_bf16 v[26:29], v[54:57], v[74:77], v[26:29]
	v_mfma_f32_16x16x32_bf16 v[34:37], v[82:85], v[74:77], v[34:37]
	v_mfma_f32_16x16x32_bf16 v[10:13], v[86:89], v[74:77], v[10:13]
	v_mfma_f32_16x16x32_bf16 v[38:41], v[70:73], v[78:81], v[38:41]
	v_mfma_f32_16x16x32_bf16 v[42:45], v[54:57], v[78:81], v[42:45]
	v_mfma_f32_16x16x32_bf16 v[46:49], v[82:85], v[78:81], v[46:49]
	v_mfma_f32_16x16x32_bf16 v[14:17], v[86:89], v[78:81], v[14:17]
	s_setprio 0
	ds_read_b128 v[74:77], v0 offset:18432
	ds_read_b128 v[78:81], v0 offset:19456
	s_waitcnt vmcnt(4) lgkmcnt(0)
	s_barrier
	s_waitcnt lgkmcnt(0)
	s_setprio 1
	v_mfma_f32_16x16x32_bf16 v[58:61], v[70:73], v[74:77], v[58:61]
	v_mfma_f32_16x16x32_bf16 v[62:65], v[54:57], v[74:77], v[62:65]
	v_mfma_f32_16x16x32_bf16 v[66:69], v[82:85], v[74:77], v[66:69]
	v_mfma_f32_16x16x32_bf16 v[50:53], v[86:89], v[74:77], v[50:53]
	v_mfma_f32_16x16x32_bf16 v[2:5], v[70:73], v[78:81], v[2:5]
	v_mfma_f32_16x16x32_bf16 v[6:9], v[54:57], v[78:81], v[6:9]
	s_setprio 0
	ds_read_b128 v[54:57], v90 offset:40960
	s_setprio 1
	v_mfma_f32_16x16x32_bf16 v[22:25], v[82:85], v[78:81], v[22:25]
	v_mfma_f32_16x16x32_bf16 v[30:33], v[86:89], v[78:81], v[30:33]
	s_setprio 0
	ds_read_b128 v[70:73], v90 offset:41984
	ds_read_b128 v[74:77], v0 offset:32768
	ds_read_b128 v[78:81], v0 offset:33792
	ds_read_b128 v[82:85], v90 offset:43008
	ds_read_b128 v[86:89], v90 offset:44032
	s_waitcnt lgkmcnt(0)
	s_setprio 1
	v_mfma_f32_16x16x32_bf16 v[18:21], v[54:57], v[74:77], v[18:21]
	v_mfma_f32_16x16x32_bf16 v[26:29], v[70:73], v[74:77], v[26:29]
	v_mfma_f32_16x16x32_bf16 v[34:37], v[82:85], v[74:77], v[34:37]
	v_mfma_f32_16x16x32_bf16 v[10:13], v[86:89], v[74:77], v[10:13]
	v_mfma_f32_16x16x32_bf16 v[38:41], v[54:57], v[78:81], v[38:41]
	v_mfma_f32_16x16x32_bf16 v[42:45], v[70:73], v[78:81], v[42:45]
	v_mfma_f32_16x16x32_bf16 v[46:49], v[82:85], v[78:81], v[46:49]
	v_mfma_f32_16x16x32_bf16 v[14:17], v[86:89], v[78:81], v[14:17]
	s_setprio 0
	ds_read_b128 v[74:77], v0 offset:34816
	ds_read_b128 v[78:81], v0 offset:35840
	s_waitcnt vmcnt(0) lgkmcnt(0)
	s_barrier
	s_waitcnt lgkmcnt(0)
	s_setprio 1
	v_mfma_f32_16x16x32_bf16 v[58:61], v[54:57], v[74:77], v[58:61]
	v_mfma_f32_16x16x32_bf16 v[62:65], v[70:73], v[74:77], v[62:65]
	v_mfma_f32_16x16x32_bf16 v[66:69], v[82:85], v[74:77], v[66:69]
	v_mfma_f32_16x16x32_bf16 v[50:53], v[86:89], v[74:77], v[50:53]
	v_mfma_f32_16x16x32_bf16 v[2:5], v[54:57], v[78:81], v[2:5]
	s_setprio 0
	ds_read_b128 v[54:57], v90 offset:8192
	s_setprio 1
	v_mfma_f32_16x16x32_bf16 v[6:9], v[70:73], v[78:81], v[6:9]
	v_mfma_f32_16x16x32_bf16 v[22:25], v[82:85], v[78:81], v[22:25]
	v_mfma_f32_16x16x32_bf16 v[30:33], v[86:89], v[78:81], v[30:33]
	s_setprio 0
	ds_read_b128 v[70:73], v90 offset:9216
	ds_read_b128 v[74:77], v0
	ds_read_b128 v[78:81], v0 offset:1024
	ds_read_b128 v[82:85], v90 offset:10240
	ds_read_b128 v[86:89], v90 offset:11264
	s_waitcnt lgkmcnt(0)
	s_setprio 1
	v_mfma_f32_16x16x32_bf16 v[18:21], v[54:57], v[74:77], v[18:21]
	v_mfma_f32_16x16x32_bf16 v[26:29], v[70:73], v[74:77], v[26:29]
	v_mfma_f32_16x16x32_bf16 v[34:37], v[82:85], v[74:77], v[34:37]
	v_mfma_f32_16x16x32_bf16 v[10:13], v[86:89], v[74:77], v[10:13]
	v_mfma_f32_16x16x32_bf16 v[38:41], v[54:57], v[78:81], v[38:41]
	v_mfma_f32_16x16x32_bf16 v[42:45], v[70:73], v[78:81], v[42:45]
	v_mfma_f32_16x16x32_bf16 v[46:49], v[82:85], v[78:81], v[46:49]
	v_mfma_f32_16x16x32_bf16 v[14:17], v[86:89], v[78:81], v[14:17]
	s_setprio 0
	ds_read_b128 v[74:77], v0 offset:2048
	ds_read_b128 v[78:81], v0 offset:3072
	s_waitcnt vmcnt(0) lgkmcnt(0)
	s_barrier
	s_setprio 1
	v_mfma_f32_16x16x32_bf16 v[58:61], v[54:57], v[74:77], v[58:61]
	global_load_dwordx4 v[90:93], v[94:95], off
	v_mfma_f32_16x16x32_bf16 v[2:5], v[54:57], v[78:81], v[2:5]
	global_load_dwordx4 v[54:57], v[94:95], off offset:128
	v_mfma_f32_16x16x32_bf16 v[62:65], v[70:73], v[74:77], v[62:65]
	v_mfma_f32_16x16x32_bf16 v[66:69], v[82:85], v[74:77], v[66:69]
	v_mfma_f32_16x16x32_bf16 v[50:53], v[86:89], v[74:77], v[50:53]
	global_load_dwordx4 v[74:77], v[94:95], off offset:64
	s_setprio 0
	s_waitcnt vmcnt(2)
	v_pk_mul_f32 v[18:19], v[18:19], v[90:91]
	s_setprio 1
	v_mfma_f32_16x16x32_bf16 v[6:9], v[70:73], v[78:81], v[6:9]
	global_load_dwordx4 v[70:73], v[94:95], off offset:192
	s_setprio 0
	s_waitcnt vmcnt(2)
	v_pk_mul_f32 v[34:35], v[34:35], v[54:55]
	v_pk_mul_f32 v[46:47], v[46:47], v[54:55]
	s_setprio 1
	v_mfma_f32_16x16x32_bf16 v[22:25], v[82:85], v[78:81], v[22:25]
	v_mul_f32_e64 v66, v66, v54
	v_mul_f32_e64 v67, v67, v55
	v_pk_mul_f32 v[36:37], v[36:37], v[56:57]
	v_pk_mul_f32 v[48:49], v[48:49], v[56:57]
	v_mfma_f32_16x16x32_bf16 v[30:33], v[86:89], v[78:81], v[30:33]
	v_mul_f32_e64 v20, v20, v92
	v_mul_f32_e64 v21, v21, v93
	s_nop 0
	v_pk_mul_f32 v[22:23], v[22:23], v[54:55]
	v_pk_mul_f32 v[54:55], v[68:69], v[56:57]
	v_pk_mul_f32 v[24:25], v[24:25], v[56:57]
	v_mov_b32_e32 v56, v196
	s_setprio 0
	s_waitcnt vmcnt(1)
	v_pk_mul_f32 v[26:27], v[26:27], v[74:75]
	v_and_b32_e32 v57, 15, v56
	v_lshrrev_b32_e32 v68, 1, v56
	v_and_b32_e32 v0, 64, v56
	v_and_or_b32 v69, v68, s2, v57
	v_pk_mul_f32 v[28:29], v[28:29], v[76:77]
	v_lshl_add_u32 v0, v0, 1, 0
	v_and_b32_e32 v68, 24, v68
	v_mul_lo_u32 v69, v69, s30
	v_add3_u32 v0, v0, v68, v69
	v_cvt_pk_bf16_f32 v18, v18, v19
	v_cvt_pk_bf16_f32 v19, v20, v21
	v_cvt_pk_bf16_f32 v20, v26, v27
	v_cvt_pk_bf16_f32 v21, v28, v29
	v_pk_mul_f32 v[38:39], v[38:39], v[90:91]
	v_pk_mul_f32 v[40:41], v[40:41], v[92:93]
	v_pk_mul_f32 v[42:43], v[42:43], v[74:75]
	v_pk_mul_f32 v[44:45], v[44:45], v[76:77]
	ds_write2_b64 v0, v[18:19], v[20:21] offset1:4
	v_cvt_pk_bf16_f32 v18, v34, v35
	v_cvt_pk_bf16_f32 v19, v36, v37
	v_pk_mul_f32 v[2:3], v[2:3], v[90:91]
	v_pk_mul_f32 v[4:5], v[4:5], v[92:93]
	v_pk_mul_f32 v[6:7], v[6:7], v[74:75]
	v_pk_mul_f32 v[8:9], v[8:9], v[76:77]
	v_pk_mul_f32 v[58:59], v[58:59], v[90:91]
	v_pk_mul_f32 v[60:61], v[60:61], v[92:93]
	v_pk_mul_f32 v[62:63], v[62:63], v[74:75]
	v_pk_mul_f32 v[64:65], v[64:65], v[76:77]
	v_cvt_pk_bf16_f32 v2, v2, v3
	v_cvt_pk_bf16_f32 v3, v4, v5
	v_cvt_pk_bf16_f32 v4, v6, v7
	v_cvt_pk_bf16_f32 v5, v8, v9
	v_add_u32_e32 v6, 0x100, v56
	s_waitcnt vmcnt(0)
	v_pk_mul_f32 v[10:11], v[10:11], v[70:71]
	v_pk_mul_f32 v[12:13], v[12:13], v[72:73]
	v_cvt_pk_bf16_f32 v10, v10, v11
	v_cvt_pk_bf16_f32 v11, v12, v13
	v_pk_mul_f32 v[14:15], v[14:15], v[70:71]
	v_pk_mul_f32 v[16:17], v[16:17], v[72:73]
	ds_write2_b64 v0, v[18:19], v[10:11] offset0:8 offset1:12
	v_cvt_pk_bf16_f32 v10, v38, v39
	v_cvt_pk_bf16_f32 v11, v40, v41
	v_cvt_pk_bf16_f32 v12, v42, v43
	v_cvt_pk_bf16_f32 v13, v44, v45
	v_add_u32_e32 v18, 0x1000, v0
	v_pk_mul_f32 v[30:31], v[30:31], v[70:71]
	v_pk_mul_f32 v[32:33], v[32:33], v[72:73]
	ds_write2_b64 v18, v[10:11], v[12:13] offset0:32 offset1:36
	v_cvt_pk_bf16_f32 v10, v46, v47
	v_cvt_pk_bf16_f32 v11, v48, v49
	v_cvt_pk_bf16_f32 v12, v14, v15
	v_cvt_pk_bf16_f32 v13, v16, v17
	v_add_u32_e32 v14, 0x2000, v0
	v_add_u32_e32 v0, 0x3000, v0
	v_pk_mul_f32 v[50:51], v[50:51], v[70:71]
	v_pk_mul_f32 v[52:53], v[52:53], v[72:73]
	ds_write2_b64 v18, v[10:11], v[12:13] offset0:40 offset1:44
	v_cvt_pk_bf16_f32 v10, v58, v59
	v_cvt_pk_bf16_f32 v11, v60, v61
	v_cvt_pk_bf16_f32 v12, v62, v63
	v_cvt_pk_bf16_f32 v13, v64, v65
	ds_write2_b64 v0, v[2:3], v[4:5] offset0:96 offset1:100
	v_cvt_pk_bf16_f32 v2, v22, v23
	v_cvt_pk_bf16_f32 v3, v24, v25
	v_cvt_pk_bf16_f32 v4, v30, v31
	v_cvt_pk_bf16_f32 v5, v32, v33
	ds_write2_b64 v14, v[10:11], v[12:13] offset0:64 offset1:68
	v_cvt_pk_bf16_f32 v10, v66, v67
	v_cvt_pk_bf16_f32 v11, v54, v55
	v_cvt_pk_bf16_f32 v12, v50, v51
	v_cvt_pk_bf16_f32 v13, v52, v53
	ds_write2_b64 v0, v[2:3], v[4:5] offset0:104 offset1:108
	v_lshlrev_b32_e32 v0, 4, v57
	v_ashrrev_i32_e32 v2, 4, v56
	ds_write2_b64 v14, v[10:11], v[12:13] offset0:72 offset1:76
	v_lshl_add_u64 v[10:11], s[0:1], 0, v[0:1]
	v_add_u32_e32 v0, 0, v0
	v_ashrrev_i32_e32 v3, 31, v2
	v_mad_u64_u32 v[4:5], s[0:1], v2, s30, v[0:1]
	v_lshlrev_b64 v[2:3], 10, v[2:3]
	s_waitcnt lgkmcnt(0)
	s_barrier
	v_lshl_add_u64 v[12:13], v[10:11], 0, v[2:3]
	ds_read_b128 v[2:5], v4
	v_ashrrev_i32_e32 v14, 4, v6
	v_mad_u64_u32 v[6:7], s[0:1], v14, s30, v[0:1]
	ds_read_b128 v[6:9], v6
	v_ashrrev_i32_e32 v15, 31, v14
	s_waitcnt lgkmcnt(1)
	global_store_dwordx4 v[12:13], v[2:5], off
	s_nop 1
	v_lshlrev_b64 v[2:3], 10, v[14:15]
	v_lshl_add_u64 v[2:3], v[10:11], 0, v[2:3]
	s_waitcnt lgkmcnt(0)
	global_store_dwordx4 v[2:3], v[6:9], off
	v_add_u32_e32 v2, 0x200, v56
	v_ashrrev_i32_e32 v2, 4, v2
	v_ashrrev_i32_e32 v3, 31, v2
	v_mad_u64_u32 v[4:5], s[0:1], v2, s30, v[0:1]
	v_lshlrev_b64 v[2:3], 10, v[2:3]
	v_add_u32_e32 v6, 0x300, v56
	v_lshl_add_u64 v[12:13], v[10:11], 0, v[2:3]
	ds_read_b128 v[2:5], v4
	v_ashrrev_i32_e32 v14, 4, v6
	v_mad_u64_u32 v[6:7], s[0:1], v14, s30, v[0:1]
	ds_read_b128 v[6:9], v6
	v_ashrrev_i32_e32 v15, 31, v14
	s_waitcnt lgkmcnt(1)
	global_store_dwordx4 v[12:13], v[2:5], off
	s_nop 1
	v_lshlrev_b64 v[2:3], 10, v[14:15]
	v_lshl_add_u64 v[2:3], v[10:11], 0, v[2:3]
	s_waitcnt lgkmcnt(0)
	global_store_dwordx4 v[2:3], v[6:9], off
	v_add_u32_e32 v2, 0x400, v56
	v_ashrrev_i32_e32 v2, 4, v2
	v_ashrrev_i32_e32 v3, 31, v2
	v_mad_u64_u32 v[4:5], s[0:1], v2, s30, v[0:1]
	v_lshlrev_b64 v[2:3], 10, v[2:3]
	v_add_u32_e32 v6, 0x500, v56
	v_lshl_add_u64 v[12:13], v[10:11], 0, v[2:3]
	ds_read_b128 v[2:5], v4
	v_ashrrev_i32_e32 v14, 4, v6
	v_mad_u64_u32 v[6:7], s[0:1], v14, s30, v[0:1]
	ds_read_b128 v[6:9], v6
	v_ashrrev_i32_e32 v15, 31, v14
	s_waitcnt lgkmcnt(1)
	global_store_dwordx4 v[12:13], v[2:5], off
	s_nop 1
	v_lshlrev_b64 v[2:3], 10, v[14:15]
	v_lshl_add_u64 v[2:3], v[10:11], 0, v[2:3]
	s_waitcnt lgkmcnt(0)
	global_store_dwordx4 v[2:3], v[6:9], off
	v_add_u32_e32 v2, 0x600, v56
	v_ashrrev_i32_e32 v2, 4, v2
	v_ashrrev_i32_e32 v3, 31, v2
	v_mad_u64_u32 v[4:5], s[0:1], v2, s30, v[0:1]
	v_lshlrev_b64 v[2:3], 10, v[2:3]
	v_add_u32_e32 v6, 0x700, v56
	v_lshl_add_u64 v[12:13], v[10:11], 0, v[2:3]
	ds_read_b128 v[2:5], v4
	v_ashrrev_i32_e32 v14, 4, v6
	v_mad_u64_u32 v[6:7], s[0:1], v14, s30, v[0:1]
	ds_read_b128 v[6:9], v6
	v_ashrrev_i32_e32 v15, 31, v14
	s_waitcnt lgkmcnt(1)
	global_store_dwordx4 v[12:13], v[2:5], off
	s_mov_b64 s[0:1], 0
	s_nop 0
	v_lshlrev_b64 v[2:3], 10, v[14:15]
	v_lshl_add_u64 v[2:3], v[10:11], 0, v[2:3]
	s_waitcnt lgkmcnt(0)
	global_store_dwordx4 v[2:3], v[6:9], off
	s_barrier
